# grid barrier leader path: dropped the two vmcnt(0) waits around the generation bump that only served the removed invalidate
# speedup vs baseline: 1.0174x; 1.0038x over previous
; DI unsigned xb_add(unsigned* p, unsigned v) { return __hip_atomic_fetch_add(p, v, __ATOMIC_RELAXED, __HIP_MEMORY_SCOPE_AGENT); }
; DI void xcd_barrier(const XcdBarrier& b) {
;     ...
;             __builtin_amdgcn_fence(__ATOMIC_ACQUIRE, "agent");
;             xb_add(&bar[XB_XGEN(b.x)], 1u);
;             asm volatile("s_waitcnt vmcnt(0)" ::: "memory");
.LBB0_150:
	s_or_b64 exec, exec, s[14:15]
	s_mov_b64 s[14:15], exec
	v_mbcnt_lo_u32_b32 v0, s14, 0
	v_mbcnt_hi_u32_b32 v0, s15, v0
	v_cmp_eq_u32_e32 vcc, 0, v0
	s_and_saveexec_b64 s[18:19], vcc
	s_cbranch_execz .LBB0_152
	s_bcnt1_i32_b64 s3, s[14:15]
	v_mov_b32_e32 v0, 0x2000
	v_mov_b32_e32 v1, s3
	global_atomic_add v0, v1, s[8:9] offset:1024

; DI unsigned xb_add(unsigned* p, unsigned v) { return __hip_atomic_fetch_add(p, v, __ATOMIC_RELAXED, __HIP_MEMORY_SCOPE_AGENT); }
; DI void xcd_barrier(const XcdBarrier& b) {
;     ...
;             __builtin_amdgcn_fence(__ATOMIC_ACQUIRE, "agent");
;             xb_add(&bar[XB_XGEN(b.x)], 1u);
;             asm volatile("s_waitcnt vmcnt(0)" ::: "memory");
.LBB0_343:
	s_or_b64 exec, exec, s[38:39]
	v_mov_b32_e32 v0, 1
	global_atomic_add v[162:163], v0, off

; DI unsigned xb_add(unsigned* p, unsigned v) { return __hip_atomic_fetch_add(p, v, __ATOMIC_RELAXED, __HIP_MEMORY_SCOPE_AGENT); }
; DI void xcd_barrier(const XcdBarrier& b) {
;     ...
;             __builtin_amdgcn_fence(__ATOMIC_ACQUIRE, "agent");
;             xb_add(&bar[XB_XGEN(b.x)], 1u);
;             asm volatile("s_waitcnt vmcnt(0)" ::: "memory");
.LBB0_407:
	s_or_b64 exec, exec, s[22:23]
	v_mov_b32_e32 v0, 1
	global_atomic_add v[162:163], v0, off

; DI unsigned xb_add(unsigned* p, unsigned v) { return __hip_atomic_fetch_add(p, v, __ATOMIC_RELAXED, __HIP_MEMORY_SCOPE_AGENT); }
; DI void xcd_barrier(const XcdBarrier& b) {
;     ...
;             __builtin_amdgcn_fence(__ATOMIC_ACQUIRE, "agent");
;             xb_add(&bar[XB_XGEN(b.x)], 1u);
;             asm volatile("s_waitcnt vmcnt(0)" ::: "memory");
.LBB0_613:
	s_or_b64 exec, exec, s[26:27]
	v_mov_b32_e32 v0, 1
	global_atomic_add v[162:163], v0, off

; DI unsigned xb_add(unsigned* p, unsigned v) { return __hip_atomic_fetch_add(p, v, __ATOMIC_RELAXED, __HIP_MEMORY_SCOPE_AGENT); }
; DI void xcd_barrier(const XcdBarrier& b) {
;     ...
;             __builtin_amdgcn_fence(__ATOMIC_ACQUIRE, "agent");
;             xb_add(&bar[XB_XGEN(b.x)], 1u);
;             asm volatile("s_waitcnt vmcnt(0)" ::: "memory");
.LBB0_763:
	s_or_b64 exec, exec, s[20:21]
	v_mov_b32_e32 v0, 1
	global_atomic_add v[162:163], v0, off

; DI unsigned xb_add(unsigned* p, unsigned v) { return __hip_atomic_fetch_add(p, v, __ATOMIC_RELAXED, __HIP_MEMORY_SCOPE_AGENT); }
; DI void xcd_barrier(const XcdBarrier& b) {
;     ...
;             __builtin_amdgcn_fence(__ATOMIC_ACQUIRE, "agent");
;             xb_add(&bar[XB_XGEN(b.x)], 1u);
;             asm volatile("s_waitcnt vmcnt(0)" ::: "memory");
.LBB0_1061:
	s_or_b64 exec, exec, s[16:17]
	v_mov_b32_e32 v0, 1
	global_atomic_add v[162:163], v0, off

; DI unsigned xb_add(unsigned* p, unsigned v) { return __hip_atomic_fetch_add(p, v, __ATOMIC_RELAXED, __HIP_MEMORY_SCOPE_AGENT); }
; DI void xcd_barrier(const XcdBarrier& b) {
;     ...
;             __builtin_amdgcn_fence(__ATOMIC_ACQUIRE, "agent");
;             xb_add(&bar[XB_XGEN(b.x)], 1u);
;             asm volatile("s_waitcnt vmcnt(0)" ::: "memory");
.LBB0_1129:
	s_or_b64 exec, exec, s[4:5]
	v_mov_b32_e32 v0, 1
	global_atomic_add v[162:163], v0, off
